# attention: at a unit's start only the K/V loads are waited for; the previous unit's last four output stores stay in flight (counted wait)
# baseline (speedup 1.0000x reference)
; #define LAS __attribute__((address_space(3)))
; __device__ __forceinline__ void attn_phase(LAS unsigned char* lds, const bf16_t* QKVZ, const float* sinks, bf16_t* OG, int G, int bid, int tid) {
;     ...
;     for (int unit = bid; unit < 1024; unit += G) {
;         const int kvh = unit & 3, n = (unit >> 2) & 31, b = unit >> 7;
;         __syncthreads();
; #pragma unroll
;         for (int i = 0; i < 4; ++i) {
;             const int c = tid + 512 * i, key = c >> 3, ch = c & 7;
;             const u32x4 kv = pkv[i], vv = pvv[i];
;             *(LAS u32x4*)(Kl + key * KP + ch * 16) = kv;
;             LAS unsigned short* vp = (LAS unsigned short*)(Vt + (ch * 8) * VP + ((key ^ (ch << 2)) * 2));
;             vp[0 * (VP / 2)] = (unsigned short)(vv.x & 0xffffu); vp[1 * (VP / 2)] = (unsigned short)(vv.x >> 16);
;             vp[2 * (VP / 2)] = (unsigned short)(vv.y & 0xffffu); vp[3 * (VP / 2)] = (unsigned short)(vv.y >> 16);
;             vp[4 * (VP / 2)] = (unsigned short)(vv.z & 0xffffu); vp[5 * (VP / 2)] = (unsigned short)(vv.z >> 16);
;             vp[6 * (VP / 2)] = (unsigned short)(vv.w & 0xffffu); vp[7 * (VP / 2)] = (unsigned short)(vv.w >> 16);
;         }
.LBB0_235:
	s_add_i32 s24, s12, s54
	s_cmpk_gt_i32 s24, 0x3ff
	s_cselect_b64 s[10:11], -1, 0
	s_and_b64 vcc, exec, s[10:11]
	s_cmp_lg_u32 s98, 0
	s_cbranch_scc1 .Lmy_att_w4
	s_waitcnt vmcnt(0) lgkmcnt(0)
	s_branch .Lmy_att_wj
.Lmy_att_w4:
	s_waitcnt vmcnt(4) lgkmcnt(0)
.Lmy_att_wj:
	s_barrier
	ds_write_b128 v130, v[8:11]
	ds_write_b16 v131, v0 offset:36864
	ds_write_b16_d16_hi v131, v0 offset:37392
	ds_write_b16 v131, v1 offset:37920
	ds_write_b16_d16_hi v131, v1 offset:38448
	ds_write_b16 v131, v2 offset:38976
	ds_write_b16_d16_hi v131, v2 offset:39504
	ds_write_b16 v131, v3 offset:40032
	ds_write_b16_d16_hi v131, v3 offset:40560
	ds_write_b128 v132, v[4:7]
	ds_write_b16 v133, v12 offset:36864
	ds_write_b16_d16_hi v133, v12 offset:37392
	ds_write_b16 v133, v13 offset:37920
	ds_write_b16_d16_hi v133, v13 offset:38448
	ds_write_b16 v133, v14 offset:38976
	ds_write_b16_d16_hi v133, v14 offset:39504
	ds_write_b16 v133, v15 offset:40032
	ds_write_b16_d16_hi v133, v15 offset:40560
	ds_write_b128 v134, v[16:19]
	ds_write_b16 v135, v20 offset:36864
	ds_write_b16_d16_hi v135, v20 offset:37392
	ds_write_b16 v135, v21 offset:37920
	ds_write_b16_d16_hi v135, v21 offset:38448
	ds_write_b16 v135, v22 offset:38976
	ds_write_b16_d16_hi v135, v22 offset:39504
	ds_write_b16 v135, v23 offset:40032
	ds_write_b16_d16_hi v135, v23 offset:40560
	ds_write_b128 v136, v[28:31]
	ds_write_b16 v137, v24 offset:36864
	ds_write_b16_d16_hi v137, v24 offset:37392
	ds_write_b16 v137, v25 offset:37920
	ds_write_b16_d16_hi v137, v25 offset:38448
	ds_write_b16 v137, v26 offset:38976
	ds_write_b16_d16_hi v137, v26 offset:39504
	ds_write_b16 v137, v27 offset:40032
	ds_write_b16_d16_hi v137, v27 offset:40560
	s_cbranch_vccnz .LBB0_245
	s_lshl_b32 s0, s24, 5
	s_and_b32 s14, s0, 0xf80
	s_addk_i32 s14, 0xff80
	s_and_b32 s13, s0, 0xfffff000
	s_lshl_b32 s0, s24, 7
	v_mov_b32_e32 v6, v73
	v_mov_b32_e32 v7, v73
	s_and_b32 s8, s0, 0x180
	v_add_u32_e32 v12, s14, v77
	v_mov_b32_e32 v4, v73
	v_mov_b32_e32 v5, v73
	v_mov_b64_e32 v[10:11], v[6:7]
	v_lshl_add_u64 v[32:33], v[74:75], 0, s[8:9]
	v_cmp_lt_i32_e32 vcc, -1, v12
	v_mov_b32_e32 v0, v73
	v_mov_b32_e32 v1, v73
	v_mov_b32_e32 v2, v73
	v_mov_b32_e32 v3, v73
	v_mov_b64_e32 v[8:9], v[4:5]
	s_and_saveexec_b64 s[0:1], vcc
	s_cbranch_execz .LBB0_238
	v_add_u32_e32 v0, s13, v12
	v_mad_i64_i32 v[12:13], s[26:27], v0, s22, v[32:33]
	global_load_dwordx4 v[8:11], v[12:13], off offset:2048
	global_load_dwordx4 v[0:3], v[12:13], off offset:2560
